# v34fwdwait
# baseline (speedup 1.0000x reference)
; #define WAIT_V(n) asm volatile("s_waitcnt vmcnt(" #n ")" ::: "memory")
; #define SB0 __builtin_amdgcn_sched_barrier(0)
; template <bool FWD>
; __device__ __forceinline__ void ret_sweep(const Params& p, int gs, int s, int g, int h, int sl, int nsegps, float lf, float lb) {
;     ...
; #pragma unroll
;     for (int mb = 0; mb < 2; ++mb)
; #pragma unroll
;       for (int nb = 0; nb < 8; ++nb) {
;         f32x4 a = T[mb][nb];
;         *(uint2*)(Ts + (nb * 16 + fr) * 264 + 32 * w + mb * 16 + fq * 4) = make_uint2(pack2(a[0], a[1]), pack2(a[2], a[3]));
;       }
;     ret_store_vt(vp, VTs, tid);
;     SB0;
;     u32x4* ypriv = (u32x4*)((char*)(Y + (long)t0 * YS + h * 512 + sl * 128) + (unsigned)(((tid >> 2) * YS + (tid & 3) * 32) * 2));
;     SB0;
;     WAIT_V(0);
;     __syncthreads();
;     f32x4 O[2][4];
; #pragma unroll
;     for (int mb = 0; mb < 2; ++mb)
; #pragma unroll
;       for (int nb = 0; nb < 4; ++nb) O[mb][nb] = f32x4{0.f, 0.f, 0.f, 0.f};
; #pragma unroll
;     for (int ks = 0; ks < 8; ++ks)
; #pragma unroll
;       for (int nb = 0; nb < 4; ++nb) {
;         bf16x8 b = *(const bf16x8*)(Ts + (64 * wv + nb * 16 + fr) * 264 + ks * 32 + fq * 8);
; #pragma unroll
;         for (int mb = 0; mb < 2; ++mb) O[mb][nb] = mfma16(qa[mb][ks], b, O[mb][nb]);
;       }
.LBB0_133:
	v_mov_b32_e32 v88, s33
	v_mbcnt_lo_u32_b32 v228, -1, 0
	v_mbcnt_hi_u32_b32 v228, -1, v228
	v_cvt_pk_bf16_f32 v89, v22, v23
	v_and_b32_e32 v250, 15, v228
	v_bfe_u32 v231, v228, 4, 2
	v_bitop3_b32 v88, v228, s49, v88 bitop3:0xc8
	v_add_u32_e32 v90, 16, v88
	v_lshlrev_b32_e32 v91, 3, v231
	v_mul_u32_u24_e32 v92, 0x210, v250
	v_cvt_pk_bf16_f32 v88, v20, v21
	v_add3_u32 v126, v90, v91, v92
	v_cvt_pk_bf16_f32 v124, v4, v5
	v_cvt_pk_bf16_f32 v125, v6, v7
	v_cvt_pk_bf16_f32 v90, v28, v29
	v_cvt_pk_bf16_f32 v91, v30, v31
	ds_write2_b64 v126, v[88:89], v[124:125] offset1:4
	v_cvt_pk_bf16_f32 v88, v8, v9
	v_cvt_pk_bf16_f32 v89, v10, v11
	v_add_u32_e32 v124, 0x2000, v126
	v_cvt_pk_bf16_f32 v92, v36, v37
	v_cvt_pk_bf16_f32 v93, v38, v39
	ds_write2_b64 v124, v[90:91], v[88:89] offset0:32 offset1:36
	v_cvt_pk_bf16_f32 v88, v12, v13
	v_cvt_pk_bf16_f32 v89, v14, v15
	v_add_u32_e32 v90, 0x4000, v126
	v_cvt_pk_bf16_f32 v94, v44, v45
	v_cvt_pk_bf16_f32 v95, v46, v47
	ds_write2_b64 v90, v[92:93], v[88:89] offset0:64 offset1:68
	v_cvt_pk_bf16_f32 v88, v16, v17
	v_cvt_pk_bf16_f32 v89, v18, v19
	v_add_u32_e32 v90, 0x6000, v126
	v_cvt_pk_bf16_f32 v116, v48, v49
	v_cvt_pk_bf16_f32 v117, v50, v51
	ds_write2_b64 v90, v[94:95], v[88:89] offset0:96 offset1:100
	v_cvt_pk_bf16_f32 v88, v24, v25
	v_cvt_pk_bf16_f32 v89, v26, v27
	v_add_u32_e32 v90, 0x8000, v126
	v_cvt_pk_bf16_f32 v118, v52, v53
	v_cvt_pk_bf16_f32 v119, v54, v55
	ds_write2_b64 v90, v[116:117], v[88:89] offset0:128 offset1:132
	v_cvt_pk_bf16_f32 v88, v32, v33
	v_cvt_pk_bf16_f32 v89, v34, v35
	v_add_u32_e32 v90, 0xa000, v126
	v_cvt_pk_bf16_f32 v120, v56, v57
	v_cvt_pk_bf16_f32 v121, v58, v59
	ds_write2_b64 v90, v[118:119], v[88:89] offset0:160 offset1:164
	v_cvt_pk_bf16_f32 v88, v40, v41
	v_cvt_pk_bf16_f32 v89, v42, v43
	v_add_u32_e32 v90, 0xc000, v126
	v_cvt_pk_bf16_f32 v122, v64, v65
	v_cvt_pk_bf16_f32 v123, v66, v67
	ds_write2_b64 v90, v[120:121], v[88:89] offset0:192 offset1:196
	v_cvt_pk_bf16_f32 v88, v60, v61
	v_cvt_pk_bf16_f32 v89, v62, v63
	v_add_u32_e32 v90, 0xe000, v126
	ds_write2_b64 v90, v[122:123], v[88:89] offset0:224 offset1:228
	v_lshlrev_b32_e32 v88, 4, v228
	v_or_b32_e32 v248, s33, v228
	v_and_b32_e32 v88, 0xf0, v88
	v_add_u32_e32 v88, s93, v88
	v_lshrrev_b32_e32 v89, 4, v248
	v_mad_u64_u32 v[90:91], s[2:3], v89, s36, v[88:89]
	v_add_u32_e32 v89, 0x200, v248
	v_lshrrev_b32_e32 v89, 4, v89
	s_waitcnt vmcnt(30)
	ds_write_b128 v90, v[204:207]
	v_mad_u64_u32 v[90:91], s[2:3], v89, s36, v[88:89]
	v_add_u32_e32 v89, 0x400, v248
	v_lshrrev_b32_e32 v89, 4, v89
	s_waitcnt vmcnt(30)
	ds_write_b128 v90, v[208:211]
	v_mad_u64_u32 v[90:91], s[2:3], v89, s36, v[88:89]
	v_add_u32_e32 v89, 0x600, v248
	v_ashrrev_i32_e32 v0, 6, v248
	v_ashrrev_i32_e32 v229, 2, v248
	v_lshrrev_b32_e32 v89, 4, v89
	v_and_b32_e32 v2, 63, v228
	v_and_b32_e32 v3, 1, v0
	v_and_b32_e32 v230, 0xffffffe0, v229
	v_and_b32_e32 v247, 48, v228
	v_mad_u64_u32 v[88:89], s[2:3], v89, s36, v[88:89]
	s_waitcnt vmcnt(28)
	ds_write_b128 v90, v[212:215]
	s_waitcnt vmcnt(28)
	ds_write_b128 v88, v[216:219]
	v_lshlrev_b32_e32 v204, 6, v3
	v_or_b32_e32 v205, v204, v250
	v_mul_u32_u24_e32 v88, 0x210, v205
	v_add3_u32 v210, 16, v247, v88
	s_waitcnt vmcnt(12)
	s_waitcnt lgkmcnt(0)
	s_barrier
	ds_read_b128 v[88:91], v210
	ds_read_b128 v[206:209], v210 offset:64
	s_waitcnt lgkmcnt(1)
	v_mfma_f32_16x16x32_bf16 v[92:95], v[220:223], v[88:91], 0
	ds_read_b128 v[116:119], v210 offset:8448
	ds_read_b128 v[124:127], v210 offset:16896
	ds_read_b128 v[148:151], v210 offset:25344
	v_mfma_f32_16x16x32_bf16 v[88:91], v[224:227], v[88:91], 0
	s_waitcnt lgkmcnt(3)
	v_mfma_f32_16x16x32_bf16 v[92:95], v[192:195], v[206:209], v[92:95]
	v_mfma_f32_16x16x32_bf16 v[88:91], v[200:203], v[206:209], v[88:91]
	ds_read_b128 v[206:209], v210 offset:8512
	s_waitcnt lgkmcnt(3)
	v_mfma_f32_16x16x32_bf16 v[120:123], v[220:223], v[116:119], 0
	v_mfma_f32_16x16x32_bf16 v[116:119], v[224:227], v[116:119], 0
	s_waitcnt lgkmcnt(0)
	v_mfma_f32_16x16x32_bf16 v[120:123], v[192:195], v[206:209], v[120:123]
	v_mfma_f32_16x16x32_bf16 v[116:119], v[200:203], v[206:209], v[116:119]
	ds_read_b128 v[206:209], v210 offset:16960
	v_mfma_f32_16x16x32_bf16 v[128:131], v[220:223], v[124:127], 0
	v_mfma_f32_16x16x32_bf16 v[124:127], v[224:227], v[124:127], 0
	s_waitcnt lgkmcnt(0)
	v_mfma_f32_16x16x32_bf16 v[128:131], v[192:195], v[206:209], v[128:131]
	v_mfma_f32_16x16x32_bf16 v[124:127], v[200:203], v[206:209], v[124:127]
	ds_read_b128 v[206:209], v210 offset:25408
	v_mfma_f32_16x16x32_bf16 v[152:155], v[220:223], v[148:151], 0
	s_waitcnt lgkmcnt(0)
	v_mfma_f32_16x16x32_bf16 v[152:155], v[192:195], v[206:209], v[152:155]
	ds_read_b128 v[192:195], v210 offset:128
	s_waitcnt lgkmcnt(0)
	v_mfma_f32_16x16x32_bf16 v[92:95], v[188:191], v[192:195], v[92:95]
	v_mfma_f32_16x16x32_bf16 v[88:91], v[196:199], v[192:195], v[88:91]
	ds_read_b128 v[192:195], v210 offset:8576
	s_waitcnt lgkmcnt(0)
	v_mfma_f32_16x16x32_bf16 v[120:123], v[188:191], v[192:195], v[120:123]
	v_mfma_f32_16x16x32_bf16 v[116:119], v[196:199], v[192:195], v[116:119]
	ds_read_b128 v[192:195], v210 offset:17024
	s_waitcnt lgkmcnt(0)
	v_mfma_f32_16x16x32_bf16 v[128:131], v[188:191], v[192:195], v[128:131]
	v_mfma_f32_16x16x32_bf16 v[124:127], v[196:199], v[192:195], v[124:127]
	ds_read_b128 v[192:195], v210 offset:25472
	s_waitcnt lgkmcnt(0)
	v_mfma_f32_16x16x32_bf16 v[152:155], v[188:191], v[192:195], v[152:155]
	ds_read_b128 v[188:191], v210 offset:192
	s_waitcnt lgkmcnt(0)
	v_mfma_f32_16x16x32_bf16 v[92:95], v[176:179], v[188:191], v[92:95]
	v_mfma_f32_16x16x32_bf16 v[88:91], v[184:187], v[188:191], v[88:91]
	ds_read_b128 v[188:191], v210 offset:8640
	s_waitcnt lgkmcnt(0)
; __device__ __forceinline__ float ex2(float x) { return __builtin_amdgcn_exp2f(x); }
; #define SB0 __builtin_amdgcn_sched_barrier(0)
; template <bool FWD>
; __device__ __forceinline__ void ret_sweep(const Params& p, int gs, int s, int g, int h, int sl, int nsegps, float lf, float lb) {
;     ...
; #pragma unroll
;     for (int ks = 0; ks < 8; ++ks)
; #pragma unroll
;       for (int nb = 0; nb < 4; ++nb) {
;         bf16x8 b = *(const bf16x8*)(Ts + (64 * wv + nb * 16 + fr) * 264 + ks * 32 + fq * 8);
; #pragma unroll
;         for (int mb = 0; mb < 2; ++mb) O[mb][nb] = mfma16(qa[mb][ks], b, O[mb][nb]);
;       }
;     SB0;
;     bf16x8 kt[2][4];
;     ret_load_kt(kt, KT + (long)(h * 128 + chunk) * 256 * 128, w, fr, fq);
;     SB0;
;     int ibase = 32 * wi + fq * 4;
;     asm volatile("" : "+v"(ibase));
; #pragma unroll
;     for (int mb = 0; mb < 2; ++mb)
; #pragma unroll
;       for (int jj = 0; jj < 4; ++jj) {
;         int i = ibase + mb * 16 + jj;
;         float sc = FWD ? ex2(lf * (float)(i + 128)) : ex2(lb * (float)(255 - i));
; #pragma unroll
;         for (int nb = 0; nb < 4; ++nb) O[mb][nb][jj] *= sc;
;       }
;     if constexpr (FWD) {
; #pragma unroll
;       for (int ks = 0; ks < 4; ++ks) {
; #pragma unroll
;         for (int nb = 0; nb < 4; ++nb) {
;           bf16x8 b = *(const bf16x8*)(VTs + (64 * wv + nb * 16 + fr) * 136 + ks * 32 + fq * 8);
; #pragma unroll
;           for (int mb = 0; mb < 2; ++mb) O[mb][nb] = mfma16(pa[mb][ks], b, O[mb][nb]);
	v_mfma_f32_16x16x32_bf16 v[120:123], v[176:179], v[188:191], v[120:123]
	v_mfma_f32_16x16x32_bf16 v[116:119], v[184:187], v[188:191], v[116:119]
	ds_read_b128 v[188:191], v210 offset:17088
	s_waitcnt lgkmcnt(0)
	v_mfma_f32_16x16x32_bf16 v[128:131], v[176:179], v[188:191], v[128:131]
	v_mfma_f32_16x16x32_bf16 v[124:127], v[184:187], v[188:191], v[124:127]
	ds_read_b128 v[188:191], v210 offset:25536
	s_waitcnt lgkmcnt(0)
	v_mfma_f32_16x16x32_bf16 v[152:155], v[176:179], v[188:191], v[152:155]
	ds_read_b128 v[176:179], v210 offset:256
	s_waitcnt lgkmcnt(0)
	v_mfma_f32_16x16x32_bf16 v[92:95], v[172:175], v[176:179], v[92:95]
	v_mfma_f32_16x16x32_bf16 v[88:91], v[180:183], v[176:179], v[88:91]
	ds_read_b128 v[176:179], v210 offset:8704
	s_waitcnt lgkmcnt(0)
	v_mfma_f32_16x16x32_bf16 v[120:123], v[172:175], v[176:179], v[120:123]
	v_mfma_f32_16x16x32_bf16 v[116:119], v[180:183], v[176:179], v[116:119]
	ds_read_b128 v[176:179], v210 offset:17152
	s_waitcnt lgkmcnt(0)
	v_mfma_f32_16x16x32_bf16 v[128:131], v[172:175], v[176:179], v[128:131]
	v_mfma_f32_16x16x32_bf16 v[124:127], v[180:183], v[176:179], v[124:127]
	ds_read_b128 v[176:179], v210 offset:25600
	s_waitcnt lgkmcnt(0)
	v_mfma_f32_16x16x32_bf16 v[152:155], v[172:175], v[176:179], v[152:155]
	ds_read_b128 v[172:175], v210 offset:320
	s_waitcnt lgkmcnt(0)
	v_mfma_f32_16x16x32_bf16 v[92:95], v[160:163], v[172:175], v[92:95]
	v_mfma_f32_16x16x32_bf16 v[88:91], v[168:171], v[172:175], v[88:91]
	ds_read_b128 v[172:175], v210 offset:8768
	s_waitcnt lgkmcnt(0)
	v_mfma_f32_16x16x32_bf16 v[120:123], v[160:163], v[172:175], v[120:123]
	v_mfma_f32_16x16x32_bf16 v[116:119], v[168:171], v[172:175], v[116:119]
	ds_read_b128 v[172:175], v210 offset:17216
	s_waitcnt lgkmcnt(0)
	v_mfma_f32_16x16x32_bf16 v[128:131], v[160:163], v[172:175], v[128:131]
	v_mfma_f32_16x16x32_bf16 v[124:127], v[168:171], v[172:175], v[124:127]
	ds_read_b128 v[172:175], v210 offset:25664
	s_waitcnt lgkmcnt(0)
	v_mfma_f32_16x16x32_bf16 v[152:155], v[160:163], v[172:175], v[152:155]
	ds_read_b128 v[160:163], v210 offset:384
	v_mfma_f32_16x16x32_bf16 v[148:151], v[224:227], v[148:151], 0
	s_waitcnt lgkmcnt(0)
	v_mfma_f32_16x16x32_bf16 v[92:95], v[156:159], v[160:163], v[92:95]
	v_mfma_f32_16x16x32_bf16 v[88:91], v[164:167], v[160:163], v[88:91]
	ds_read_b128 v[160:163], v210 offset:8832
	v_mfma_f32_16x16x32_bf16 v[148:151], v[200:203], v[206:209], v[148:151]
	s_waitcnt lgkmcnt(0)
	v_mfma_f32_16x16x32_bf16 v[120:123], v[156:159], v[160:163], v[120:123]
	v_mfma_f32_16x16x32_bf16 v[116:119], v[164:167], v[160:163], v[116:119]
	ds_read_b128 v[160:163], v210 offset:17280
	v_mfma_f32_16x16x32_bf16 v[148:151], v[196:199], v[192:195], v[148:151]
	s_waitcnt lgkmcnt(0)
	v_mfma_f32_16x16x32_bf16 v[128:131], v[156:159], v[160:163], v[128:131]
	v_mfma_f32_16x16x32_bf16 v[124:127], v[164:167], v[160:163], v[124:127]
	ds_read_b128 v[160:163], v210 offset:25728
	v_mfma_f32_16x16x32_bf16 v[148:151], v[184:187], v[188:191], v[148:151]
	s_waitcnt lgkmcnt(0)
	v_mfma_f32_16x16x32_bf16 v[152:155], v[156:159], v[160:163], v[152:155]
	ds_read_b128 v[156:159], v210 offset:448
	v_mfma_f32_16x16x32_bf16 v[148:151], v[180:183], v[176:179], v[148:151]
	v_mfma_f32_16x16x32_bf16 v[148:151], v[168:171], v[172:175], v[148:151]
	s_waitcnt lgkmcnt(0)
	v_mfma_f32_16x16x32_bf16 v[168:171], v[140:143], v[156:159], v[92:95]
	v_mfma_f32_16x16x32_bf16 v[156:159], v[144:147], v[156:159], v[88:91]
	s_nop 2
	ds_read_b128 v[88:91], v210 offset:8896
	v_mfma_f32_16x16x32_bf16 v[148:151], v[164:167], v[160:163], v[148:151]
	s_waitcnt lgkmcnt(0)
	v_mfma_f32_16x16x32_bf16 v[172:175], v[140:143], v[88:91], v[120:123]
	v_mfma_f32_16x16x32_bf16 v[160:163], v[144:147], v[88:91], v[116:119]
	ds_read_b128 v[88:91], v210 offset:17344
	s_waitcnt lgkmcnt(0)
	v_mfma_f32_16x16x32_bf16 v[176:179], v[140:143], v[88:91], v[128:131]
	v_mfma_f32_16x16x32_bf16 v[164:167], v[144:147], v[88:91], v[124:127]
	ds_read_b128 v[88:91], v210 offset:25792
	s_waitcnt lgkmcnt(0)
	v_mfma_f32_16x16x32_bf16 v[140:143], v[140:143], v[88:91], v[152:155]
	v_mfma_f32_16x16x32_bf16 v[180:183], v[144:147], v[88:91], v[148:151]
	v_lshlrev_b32_e32 v0, 13, v0
	v_lshlrev_b32_e32 v88, 8, v250
	s_add_u32 s2, s96, s6
	v_or3_b32 v0, v0, v88, v247
	s_addc_u32 s3, s97, s7
	v_lshl_add_u64 v[88:89], s[2:3], 0, v[0:1]
	s_mov_b32 s2, 0x10800000
	v_add_co_u32_e32 v90, vcc, s2, v88
	s_mov_b32 s2, 0x10801000
	s_nop 0
	v_addc_co_u32_e32 v91, vcc, 0, v89, vcc
	v_add_co_u32_e32 v92, vcc, s2, v88
	s_nop 1
	v_addc_co_u32_e32 v93, vcc, 0, v89, vcc
	global_load_dwordx4 v[124:127], v[90:91], off offset:64
	global_load_dwordx4 v[116:119], v[90:91], off offset:128
	global_load_dwordx4 v[148:151], v[92:93], off offset:-4096
	s_nop 0
	global_load_dwordx4 v[88:91], v[90:91], off offset:192
	s_nop 0
	global_load_dwordx4 v[152:155], v[92:93], off
	global_load_dwordx4 v[128:131], v[92:93], off offset:64
	global_load_dwordx4 v[120:123], v[92:93], off offset:128
	s_nop 0
	global_load_dwordx4 v[92:95], v[92:93], off offset:192
	v_lshl_or_b32 v144, v231, 2, v230
	v_mov_b32_e32 v0, v144
	s_nop 0
	v_add_u32_e32 v145, 0x80, v0
	v_cvt_f32_i32_e32 v145, v145
	v_mul_f32_e32 v145, v251, v145
	v_exp_f32_e32 v146, v145
	v_add_u32_e32 v145, 0x81, v0
	v_cvt_f32_i32_e32 v145, v145
	v_mul_f32_e32 v145, v251, v145
	v_exp_f32_e32 v147, v145
	v_add_u32_e32 v145, 0x82, v0
	v_cvt_f32_i32_e32 v145, v145
	v_pk_mul_f32 v[168:169], v[168:169], v[146:147]
	v_pk_mul_f32 v[172:173], v[172:173], v[146:147]
	v_mul_f32_e32 v145, v251, v145
	v_exp_f32_e32 v184, v145
	v_add_u32_e32 v145, 0x83, v0
	v_cvt_f32_i32_e32 v145, v145
	v_pk_mul_f32 v[176:177], v[176:177], v[146:147]
	v_pk_mul_f32 v[140:141], v[140:141], v[146:147]
	v_mul_f32_e32 v145, v251, v145
	v_exp_f32_e32 v185, v145
	v_add_u32_e32 v145, 0x90, v0
	v_cvt_f32_i32_e32 v145, v145
	v_pk_mul_f32 v[170:171], v[170:171], v[184:185]
	v_pk_mul_f32 v[174:175], v[174:175], v[184:185]
	v_mul_f32_e32 v145, v251, v145
	v_exp_f32_e32 v146, v145
	v_add_u32_e32 v145, 0x91, v0
	v_cvt_f32_i32_e32 v145, v145
	v_pk_mul_f32 v[178:179], v[178:179], v[184:185]
	v_pk_mul_f32 v[142:143], v[142:143], v[184:185]
	v_mul_f32_e32 v145, v251, v145
	v_exp_f32_e32 v147, v145
	v_add_u32_e32 v145, 0x92, v0
	v_add_u32_e32 v0, 0x93, v0
	v_cvt_f32_i32_e32 v145, v145
	v_cvt_f32_i32_e32 v0, v0
	v_pk_mul_f32 v[156:157], v[156:157], v[146:147]
	v_pk_mul_f32 v[160:161], v[160:161], v[146:147]
	v_mul_f32_e32 v145, v251, v145
	v_mul_f32_e32 v0, v251, v0
	v_exp_f32_e32 v184, v145
	v_exp_f32_e32 v185, v0
	v_mul_u32_u24_e32 v0, 0x110, v205
	v_add3_u32 v0, s93, v247, v0
	v_pk_mul_f32 v[164:165], v[164:165], v[146:147]
	v_pk_mul_f32 v[158:159], v[158:159], v[184:185]
	v_pk_mul_f32 v[162:163], v[162:163], v[184:185]
	v_pk_mul_f32 v[166:167], v[166:167], v[184:185]
	v_pk_mul_f32 v[182:183], v[182:183], v[184:185]
	ds_read_b128 v[184:187], v0
	s_waitcnt vmcnt(19) lgkmcnt(0)
; __device__ __forceinline__ float bf2f(u16 b) { return __uint_as_float(((unsigned)b) << 16); }
; #define SB0 __builtin_amdgcn_sched_barrier(0)
; template <bool FWD>
; __device__ __forceinline__ void ret_sweep(const Params& p, int gs, int s, int g, int h, int sl, int nsegps, float lf, float lb) {
;     ...
;     if constexpr (FWD) {
; #pragma unroll
;       for (int ks = 0; ks < 4; ++ks) {
; #pragma unroll
;         for (int nb = 0; nb < 4; ++nb) {
;           bf16x8 b = *(const bf16x8*)(VTs + (64 * wv + nb * 16 + fr) * 136 + ks * 32 + fq * 8);
; #pragma unroll
;           for (int mb = 0; mb < 2; ++mb) O[mb][nb] = mfma16(pa[mb][ks], b, O[mb][nb]);
;         }
;       }
;     }
;     SB0;
;     if constexpr (!FWD) {
; #pragma unroll
;       for (int q = 0; q < 4; ++q) {
;         u32x4 pk;
; #pragma unroll
;         for (int e2 = 0; e2 < 4; ++e2) {
;           int e = q * 8 + e2 * 2;
;           pk[e2] = pack2(O[e >> 4][e & 3][(e >> 2) & 3], O[(e + 1) >> 4][(e + 1) & 3][((e + 1) >> 2) & 3]);
;         }
;         ypriv[q] = pk;
;       }
;     } else {
; #pragma unroll
;       for (int mb = 0; mb < 2; ++mb)
; #pragma unroll
;         for (int jj = 0; jj < 4; ++jj) {
;           int i = 32 * wi + mb * 16 + fq * 4 + jj;
;           u16* yp = (u16*)((char*)(Y + (long)t0 * YS + h * 512 + sl * 128) + (unsigned)((i * YS + 64 * wv + fr) * 2));
;           float s1 = 0.f, s2 = 0.f;
; #pragma unroll
;           for (int nb = 0; nb < 4; ++nb) {
;             int e = (mb * 4 + jj) * 4 + nb;
;             unsigned pw = yb[e >> 3][(e >> 1) & 3];
;             float prev = bf2f((u16)((e & 1) ? (pw >> 16) : (pw & 0xffffu)));
;             float v = O[mb][nb][jj] + prev;
;             yp[nb * 16] = f2bf(v);
;             s1 += v; s2 += v * v;
;           }
; #pragma unroll
;           for (int o = 1; o < 16; o <<= 1) { s1 += shx(s1, o, lane); s2 += shx(s2, o, lane); }
;           if (fr == 0) { red[(i * 2 + wv) * 2] = s1; red[(i * 2 + wv) * 2 + 1] = s2; }
	v_mfma_f32_16x16x32_bf16 v[168:171], v[132:135], v[184:187], v[168:171]
	v_mul_f32_e64 v180, v180, v146
	v_mul_f32_e64 v181, v181, v147
	s_waitcnt vmcnt(15)
	v_mfma_f32_16x16x32_bf16 v[156:159], v[136:139], v[184:187], v[156:159]
	ds_read_b128 v[184:187], v0 offset:4352
	s_waitcnt lgkmcnt(0)
	v_mfma_f32_16x16x32_bf16 v[172:175], v[132:135], v[184:187], v[172:175]
	v_mfma_f32_16x16x32_bf16 v[160:163], v[136:139], v[184:187], v[160:163]
	ds_read_b128 v[184:187], v0 offset:8704
	s_waitcnt lgkmcnt(0)
	v_mfma_f32_16x16x32_bf16 v[176:179], v[132:135], v[184:187], v[176:179]
	v_mfma_f32_16x16x32_bf16 v[164:167], v[136:139], v[184:187], v[164:167]
	ds_read_b128 v[184:187], v0 offset:13056
	s_waitcnt lgkmcnt(0)
	v_mfma_f32_16x16x32_bf16 v[132:135], v[132:135], v[184:187], v[140:143]
	s_nop 2
	ds_read_b128 v[140:143], v0 offset:64
	s_waitcnt lgkmcnt(0)
	v_mfma_f32_16x16x32_bf16 v[168:171], v[104:107], v[140:143], v[168:171]
	s_waitcnt vmcnt(14)
	v_mfma_f32_16x16x32_bf16 v[140:143], v[112:115], v[140:143], v[156:159]
	s_nop 2
	ds_read_b128 v[156:159], v0 offset:4416
	s_waitcnt lgkmcnt(0)
	v_mfma_f32_16x16x32_bf16 v[172:175], v[104:107], v[156:159], v[172:175]
	v_mfma_f32_16x16x32_bf16 v[156:159], v[112:115], v[156:159], v[160:163]
	s_nop 2
	ds_read_b128 v[160:163], v0 offset:8768
	s_waitcnt lgkmcnt(0)
	v_mfma_f32_16x16x32_bf16 v[176:179], v[104:107], v[160:163], v[176:179]
	v_mfma_f32_16x16x32_bf16 v[160:163], v[112:115], v[160:163], v[164:167]
	s_nop 2
	ds_read_b128 v[164:167], v0 offset:13120
	s_waitcnt lgkmcnt(0)
	v_mfma_f32_16x16x32_bf16 v[104:107], v[104:107], v[164:167], v[132:135]
	s_nop 2
	ds_read_b128 v[132:135], v0 offset:128
	v_mfma_f32_16x16x32_bf16 v[136:139], v[136:139], v[184:187], v[180:183]
	v_mfma_f32_16x16x32_bf16 v[112:115], v[112:115], v[164:167], v[136:139]
	s_waitcnt lgkmcnt(0)
	v_mfma_f32_16x16x32_bf16 v[136:139], v[100:103], v[132:135], v[168:171]
	s_waitcnt vmcnt(13)
	v_mfma_f32_16x16x32_bf16 v[140:143], v[108:111], v[132:135], v[140:143]
	ds_read_b128 v[132:135], v0 offset:4480
	s_waitcnt lgkmcnt(0)
	v_mfma_f32_16x16x32_bf16 v[164:167], v[100:103], v[132:135], v[172:175]
	v_mfma_f32_16x16x32_bf16 v[156:159], v[108:111], v[132:135], v[156:159]
	ds_read_b128 v[132:135], v0 offset:8832
	s_waitcnt lgkmcnt(0)
	v_mfma_f32_16x16x32_bf16 v[168:171], v[100:103], v[132:135], v[176:179]
	v_mfma_f32_16x16x32_bf16 v[160:163], v[108:111], v[132:135], v[160:163]
	ds_read_b128 v[132:135], v0 offset:13184
	s_waitcnt lgkmcnt(0)
	v_mfma_f32_16x16x32_bf16 v[172:175], v[100:103], v[132:135], v[104:107]
	ds_read_b128 v[100:103], v0 offset:192
	v_mfma_f32_16x16x32_bf16 v[176:179], v[108:111], v[132:135], v[112:115]
	ds_read_b128 v[108:111], v0 offset:8896
	s_waitcnt lgkmcnt(1)
	v_mfma_f32_16x16x32_bf16 v[132:135], v[84:87], v[100:103], v[136:139]
	s_waitcnt vmcnt(12)
	v_mfma_f32_16x16x32_bf16 v[104:107], v[96:99], v[100:103], v[140:143]
	ds_read_b128 v[100:103], v0 offset:4544
	s_waitcnt lgkmcnt(0)
	v_mfma_f32_16x16x32_bf16 v[112:115], v[84:87], v[100:103], v[164:167]
	v_mfma_f32_16x16x32_bf16 v[100:103], v[96:99], v[100:103], v[156:159]
	s_nop 2
	ds_read_b128 v[156:159], v0 offset:13248
	v_mfma_f32_16x16x32_bf16 v[136:139], v[84:87], v[108:111], v[168:171]
	v_mfma_f32_16x16x32_bf16 v[108:111], v[96:99], v[108:111], v[160:163]
	s_waitcnt lgkmcnt(0)
	v_mfma_f32_16x16x32_bf16 v[140:143], v[84:87], v[156:159], v[172:175]
	v_mfma_f32_16x16x32_bf16 v[84:87], v[96:99], v[156:159], v[176:179]
	v_readlane_b32 s2, v254, 45
	s_waitcnt vmcnt(8)
	v_and_b32_e32 v96, 0xffff0000, v81
	v_lshlrev_b32_e32 v81, 16, v81
	v_lshl_add_u32 v97, v3, 3, s2
	v_lshlrev_b32_e32 v3, 16, v80
	v_and_b32_e32 v80, 0xffff0000, v80
	v_mov_b32_e32 v156, v112
	v_mov_b32_e32 v157, v136
	v_pk_add_f32 v[156:157], v[156:157], v[80:81]
	v_add_f32_e32 v98, v132, v3
	v_pk_mul_f32 v[158:159], v[156:157], v[156:157]
	v_mov_b32_e32 v99, v136
	v_mov_b32_e32 v160, v1
	v_mov_b32_e32 v161, v81
	v_mul_f32_e32 v3, v98, v98
	v_lshlrev_b32_e32 v132, 2, v2
	v_pk_add_f32 v[160:161], v[98:99], v[160:161]
	v_mov_b32_e32 v2, v136
	v_pk_mov_b32 v[80:81], v[80:81], v[158:159] op_sel:[1,0]
	v_pk_mul_f32 v[158:159], v[156:157], v[160:161]
	v_pk_add_f32 v[2:3], v[2:3], v[80:81]
	v_pk_add_f32 v[80:81], v[156:157], v[160:161]
	v_add_f32_e32 v146, v140, v96
	v_mov_b32_e32 v81, v159
	v_mul_f32_e32 v147, v146, v146
	v_pk_add_f32 v[2:3], v[80:81], v[2:3]
	v_xor_b32_e32 v96, 4, v132
	v_pk_add_f32 v[2:3], v[2:3], v[146:147]
	ds_bpermute_b32 v80, v96, v2
	ds_bpermute_b32 v81, v96, v3
	v_xor_b32_e32 v99, 8, v132
	v_xor_b32_e32 v112, 16, v132
	s_movk_i32 s2, 0x1080
	v_mul_lo_u32 v145, v144, s2
	s_waitcnt lgkmcnt(0)
	v_pk_add_f32 v[2:3], v[2:3], v[80:81]
	ds_bpermute_b32 v80, v99, v2
	ds_bpermute_b32 v81, v99, v3
	v_or_b32_e32 v0, v205, v145
	s_add_u32 s2, s96, s38
	v_lshlrev_b32_e32 v0, 1, v0
	s_addc_u32 s3, s97, s35
	s_waitcnt lgkmcnt(0)
	v_pk_add_f32 v[2:3], v[2:3], v[80:81]
	ds_bpermute_b32 v80, v112, v2
	ds_bpermute_b32 v81, v112, v3
	v_lshl_add_u64 v[158:159], s[2:3], 0, v[0:1]
	v_cvt_pk_bf16_f32 v0, v98, s0
	v_xor_b32_e32 v98, 32, v132
	v_add_co_u32_e32 v158, vcc, s37, v158
	s_waitcnt lgkmcnt(0)
	v_pk_add_f32 v[2:3], v[2:3], v[80:81]
	ds_bpermute_b32 v80, v98, v2
	ds_bpermute_b32 v81, v98, v3
	v_addc_co_u32_e32 v159, vcc, 0, v159, vcc
	global_store_short v[158:159], v0, off
	v_cvt_pk_bf16_f32 v0, v146, s0
	global_store_short v[158:159], v0, off offset:96
	v_cvt_pk_bf16_f32 v0, v156, s0
	v_cmp_eq_u32_e64 s[4:5], 0, v250
	global_store_short v[158:159], v0, off offset:32
	v_cvt_pk_bf16_f32 v0, v157, s0
	v_lshl_add_u32 v97, v144, 4, v97
	global_store_short v[158:159], v0, off offset:64
	s_and_saveexec_b64 s[2:3], s[4:5]
	s_cbranch_execz .LBB0_135
	s_waitcnt lgkmcnt(0)
	v_pk_add_f32 v[2:3], v[2:3], v[80:81]
	ds_write_b64 v97, v[2:3]
